# speedup vs baseline: 1.0178x; 1.0096x over previous
; __device__ __forceinline__ int otid() { int t = threadIdx.x; asm volatile("" : "+v"(t)); return t; }
; __device__ void transpose_tile(const float* __restrict__ src, u16* __restrict__ dst, int K, int N, int k0, int n0,
;                                const float* __restrict__ kscale) {
;     ...
;   const int tid = otid();
;   {
;     const int kk = tid >> 4, nn4 = (tid & 15) * 4;
;     #pragma unroll
;     for (int h = 0; h < 2; ++h) {
;       const int k = kk + h * 32;
;       float4 v = *reinterpret_cast<const float4*>(src + (size_t)(k0 + k) * N + n0 + nn4);
;       float sc = kscale ? kscale[k0 + k] : 1.f;
;       tile[k * 65 + nn4 + 0] = v.x * sc; tile[k * 65 + nn4 + 1] = v.y * sc;
;       tile[k * 65 + nn4 + 2] = v.z * sc; tile[k * 65 + nn4 + 3] = v.w * sc;
;     }
;   }
;   __syncthreads();
;   {
;     const int nn = tid >> 3, kk8 = (tid & 7) * 8;
;     v4u o;
;     o.x = pk2(tile[(kk8 + 0) * 65 + nn], tile[(kk8 + 1) * 65 + nn]);
;     o.y = pk2(tile[(kk8 + 2) * 65 + nn], tile[(kk8 + 3) * 65 + nn]);
;     o.z = pk2(tile[(kk8 + 4) * 65 + nn], tile[(kk8 + 5) * 65 + nn]);
;     o.w = pk2(tile[(kk8 + 6) * 65 + nn], tile[(kk8 + 7) * 65 + nn]);
;     *reinterpret_cast<v4u*>(dst + (size_t)(n0 + nn) * K + k0 + kk8) = o;
; __device__ void phase0(const Params& p) {
;     ...
;   for (int t = b; t < T_ALL; t += G) {
;     int u = t;
;     if (u < T_WIN) { transpose_tile(p.w_in, (u16*)(ws + OFF_WIN), 2048, NIN, (u % 32) * 64, (u / 32) * 64, p.g_pre); continue; }
.LBB0_20:
	s_or_b64 exec, exec, s[4:5]
	v_mov_b32_e32 v1, 0x20000
	s_load_dwordx16 s[36:51], s[0:1], 0x0
	s_load_dwordx16 s[52:67], s[0:1], 0x40
	s_waitcnt lgkmcnt(0)
	s_barrier
	ds_read_b96 v[2:4], v1
	v_mov_b32_e32 v1, v194
	s_cmpk_gt_i32 s2, 0x237f
	s_waitcnt lgkmcnt(0)
	v_readfirstlane_b32 s0, v2
	v_readfirstlane_b32 s87, v3
	v_readfirstlane_b32 s86, v4
	v_writelane_b32 v254, s0, 0
	s_cbranch_scc1 .LBB0_51
	s_add_u32 s3, s30, 0x4600000
	s_addc_u32 s24, s31, 0
	s_add_u32 s4, s30, 0x4500000
	s_addc_u32 s5, s31, 0
	s_add_u32 s6, s30, 0x3d00000
	s_addc_u32 s7, s31, 0
	s_add_u32 s8, s30, 0x3500000
	s_addc_u32 s9, s31, 0
	s_add_u32 s10, s30, 0x3100000
	s_addc_u32 s11, s31, 0
	s_add_u32 s12, s30, 0x2900000
	s_addc_u32 s13, s31, 0
	s_add_u32 s14, s30, 0x100000
	s_addc_u32 s15, s31, 0
	s_cmp_lg_u64 s[44:45], 0
	s_cselect_b64 s[18:19], -1, 0
	s_lshl_b32 s25, s2, 6
	s_lshl_b32 s34, s33, 6
	s_lshl_b32 s35, s2, 5
	s_lshl_b32 s76, s33, 5
	s_lshl_b32 s77, s2, 4
	s_lshl_b32 s78, s33, 4
	s_lshl_b32 s79, s2, 1
	s_lshl_b32 s80, s33, 1
	s_lshl_b32 s81, s2, 2
	s_lshl_b32 s82, s33, 2
	s_mov_b32 s21, 0
	v_mov_b32_e32 v11, 0
	s_movk_i32 s83, 0x104
	s_mov_b32 s84, 0xa000
	v_cndmask_b32_e64 v13, 0, 1, s[18:19]
	s_mov_b32 s85, s2
	v_lshrrev_b32_e32 v119, 4, v194
	v_and_b32_e32 v118, 15, v194
	v_lshlrev_b32_e32 v118, 4, v118
	v_mul_u32_u24_e32 v100, 0xa000, v119
	v_add_u32_e32 v100, v100, v118
	v_lshlrev_b32_e32 v101, 2, v119
	v_mul_u32_u24_e32 v102, 0x104, v119
	v_add_u32_e32 v102, v102, v118
	v_add_u32_e32 v103, 0x4100, v102
	v_add_u32_e32 v104, 0x8200, v102
	v_add_u32_e32 v105, 0xc300, v102
	v_add_u32_e32 v106, 0x2080, v102
	v_add_u32_e32 v107, 0x2080, v103
	v_add_u32_e32 v108, 0x2080, v104
	v_add_u32_e32 v109, 0x2080, v105
	v_lshrrev_b32_e32 v119, 3, v194
	v_and_b32_e32 v118, 7, v194
	v_lshlrev_b32_e32 v118, 3, v118
	v_mul_u32_u24_e32 v110, 0x104, v118
	v_lshl_add_u32 v110, v119, 2, v110
	v_add_u32_e32 v111, 0x4100, v110
	v_add_u32_e32 v112, 0x8200, v110
	v_add_u32_e32 v113, 0xc300, v110
	v_add_u32_e32 v114, 0x400, v110
	v_add_u32_e32 v115, 0x400, v111
	v_add_u32_e32 v116, 0x400, v112
	v_add_u32_e32 v117, 0x400, v113
	v_lshlrev_b32_e32 v118, 1, v118
	v_lshl_add_u32 v118, v119, 12, v118
; __device__ __forceinline__ int otid() { int t = threadIdx.x; asm volatile("" : "+v"(t)); return t; }
; __device__ void transpose_tile(const float* __restrict__ src, u16* __restrict__ dst, int K, int N, int k0, int n0,
;                                const float* __restrict__ kscale) {
;   float* tile = reinterpret_cast<float*>(g_smem);
;   const int tid = otid();
;   {
;     const int kk = tid >> 4, nn4 = (tid & 15) * 4;
;     #pragma unroll
;     for (int h = 0; h < 2; ++h) {
;       const int k = kk + h * 32;
;       float4 v = *reinterpret_cast<const float4*>(src + (size_t)(k0 + k) * N + n0 + nn4);
;       float sc = kscale ? kscale[k0 + k] : 1.f;
;       tile[k * 65 + nn4 + 0] = v.x * sc; tile[k * 65 + nn4 + 1] = v.y * sc;
;       tile[k * 65 + nn4 + 2] = v.z * sc; tile[k * 65 + nn4 + 3] = v.w * sc;
;     }
;   }
;   __syncthreads();
;   {
;     const int nn = tid >> 3, kk8 = (tid & 7) * 8;
;     v4u o;
;     o.x = pk2(tile[(kk8 + 0) * 65 + nn], tile[(kk8 + 1) * 65 + nn]);
;     o.y = pk2(tile[(kk8 + 2) * 65 + nn], tile[(kk8 + 3) * 65 + nn]);
;     o.z = pk2(tile[(kk8 + 4) * 65 + nn], tile[(kk8 + 5) * 65 + nn]);
;     o.w = pk2(tile[(kk8 + 6) * 65 + nn], tile[(kk8 + 7) * 65 + nn]);
;     *reinterpret_cast<v4u*>(dst + (size_t)(n0 + nn) * K + k0 + kk8) = o;
;   }
;   __syncthreads();
; }
; __device__ void phase0(const Params& p) {
;     ...
;   for (int t = b; t < T_ALL; t += G) {
;     int u = t;
;     if (u < T_WIN) { transpose_tile(p.w_in, (u16*)(ws + OFF_WIN), 2048, NIN, (u % 32) * 64, (u / 32) * 64, p.g_pre); continue; }
.Lp0w_loop:
	s_mul_i32 s92, s33, 3
	s_add_i32 s92, s92, s85
	s_cmpk_gt_i32 s92, 0x13ff
	s_cbranch_scc1 .Lp0w_done
	s_mov_b32 s93, s85
	s_and_b32 s100, s93, 31
	s_lshl_b32 s100, s100, 6
	s_lshr_b32 s101, s93, 5
	s_lshl_b32 s101, s101, 6
	s_mul_i32 s94, s100, 0xa000
	s_lshl_b32 s95, s101, 2
	s_add_i32 s94, s94, s95
	s_lshl_b32 s95, s100, 2
	s_lshl_b32 s96, s101, 12
	s_lshl_b32 s92, s100, 1
	s_add_i32 s96, s96, s92
	v_add_u32_e32 v168, s94, v100
	v_add_u32_e32 v172, 0x140000, v168
	v_add_u32_e32 v176, s95, v101
	global_load_dwordx4 v[120:123], v168, s[46:47]
	global_load_dwordx4 v[124:127], v172, s[46:47]
	global_load_dword v152, v176, s[44:45]
	global_load_dword v154, v176, s[44:45] offset:128
	s_add_i32 s93, s93, s33
	s_and_b32 s100, s93, 31
	s_lshl_b32 s100, s100, 6
	s_lshr_b32 s101, s93, 5
	s_lshl_b32 s101, s101, 6
	s_mul_i32 s94, s100, 0xa000
	s_lshl_b32 s95, s101, 2
	s_add_i32 s94, s94, s95
	s_lshl_b32 s95, s100, 2
	s_lshl_b32 s97, s101, 12
	s_lshl_b32 s92, s100, 1
	s_add_i32 s97, s97, s92
	v_add_u32_e32 v169, s94, v100
	v_add_u32_e32 v173, 0x140000, v169
	v_add_u32_e32 v177, s95, v101
	global_load_dwordx4 v[128:131], v169, s[46:47]
	global_load_dwordx4 v[132:135], v173, s[46:47]
	global_load_dword v156, v177, s[44:45]
	global_load_dword v158, v177, s[44:45] offset:128
	s_add_i32 s93, s93, s33
	s_and_b32 s100, s93, 31
	s_lshl_b32 s100, s100, 6
	s_lshr_b32 s101, s93, 5
	s_lshl_b32 s101, s101, 6
	s_mul_i32 s94, s100, 0xa000
	s_lshl_b32 s95, s101, 2
	s_add_i32 s94, s94, s95
	s_lshl_b32 s95, s100, 2
	s_lshl_b32 s98, s101, 12
	s_lshl_b32 s92, s100, 1
	s_add_i32 s98, s98, s92
	v_add_u32_e32 v170, s94, v100
	v_add_u32_e32 v174, 0x140000, v170
	v_add_u32_e32 v178, s95, v101
	global_load_dwordx4 v[136:139], v170, s[46:47]
	global_load_dwordx4 v[140:143], v174, s[46:47]
	global_load_dword v160, v178, s[44:45]
	global_load_dword v162, v178, s[44:45] offset:128
	s_add_i32 s93, s93, s33
	s_and_b32 s100, s93, 31
	s_lshl_b32 s100, s100, 6
	s_lshr_b32 s101, s93, 5
	s_lshl_b32 s101, s101, 6
	s_mul_i32 s94, s100, 0xa000
	s_lshl_b32 s95, s101, 2
	s_add_i32 s94, s94, s95
	s_lshl_b32 s95, s100, 2
	s_lshl_b32 s99, s101, 12
	s_lshl_b32 s92, s100, 1
	s_add_i32 s99, s99, s92
	v_add_u32_e32 v171, s94, v100
	v_add_u32_e32 v175, 0x140000, v171
	v_add_u32_e32 v179, s95, v101
	global_load_dwordx4 v[144:147], v171, s[46:47]
	global_load_dwordx4 v[148:151], v175, s[46:47]
	global_load_dword v164, v179, s[44:45]
	global_load_dword v166, v179, s[44:45] offset:128
	s_waitcnt vmcnt(12)
	v_pk_mul_f32 v[120:121], v[120:121], v[152:153] op_sel_hi:[1,0]
	v_pk_mul_f32 v[122:123], v[122:123], v[152:153] op_sel_hi:[1,0]
	v_pk_mul_f32 v[124:125], v[124:125], v[154:155] op_sel_hi:[1,0]
	v_pk_mul_f32 v[126:127], v[126:127], v[154:155] op_sel_hi:[1,0]
	ds_write2_b32 v102, v120, v121 offset1:1
	ds_write2_b32 v102, v122, v123 offset0:2 offset1:3
	ds_write2_b32 v106, v124, v125 offset1:1
	ds_write2_b32 v106, v126, v127 offset0:2 offset1:3
	s_waitcnt vmcnt(8)
	v_pk_mul_f32 v[128:129], v[128:129], v[156:157] op_sel_hi:[1,0]
	v_pk_mul_f32 v[130:131], v[130:131], v[156:157] op_sel_hi:[1,0]
	v_pk_mul_f32 v[132:133], v[132:133], v[158:159] op_sel_hi:[1,0]
	v_pk_mul_f32 v[134:135], v[134:135], v[158:159] op_sel_hi:[1,0]
	ds_write2_b32 v103, v128, v129 offset1:1
	ds_write2_b32 v103, v130, v131 offset0:2 offset1:3
	ds_write2_b32 v107, v132, v133 offset1:1
	ds_write2_b32 v107, v134, v135 offset0:2 offset1:3
	s_waitcnt vmcnt(4)
	v_pk_mul_f32 v[136:137], v[136:137], v[160:161] op_sel_hi:[1,0]
	v_pk_mul_f32 v[138:139], v[138:139], v[160:161] op_sel_hi:[1,0]
	v_pk_mul_f32 v[140:141], v[140:141], v[162:163] op_sel_hi:[1,0]
	v_pk_mul_f32 v[142:143], v[142:143], v[162:163] op_sel_hi:[1,0]
	ds_write2_b32 v104, v136, v137 offset1:1
	ds_write2_b32 v104, v138, v139 offset0:2 offset1:3
	ds_write2_b32 v108, v140, v141 offset1:1
	ds_write2_b32 v108, v142, v143 offset0:2 offset1:3
	s_waitcnt vmcnt(0)
	v_pk_mul_f32 v[144:145], v[144:145], v[164:165] op_sel_hi:[1,0]
	v_pk_mul_f32 v[146:147], v[146:147], v[164:165] op_sel_hi:[1,0]
	v_pk_mul_f32 v[148:149], v[148:149], v[166:167] op_sel_hi:[1,0]
	v_pk_mul_f32 v[150:151], v[150:151], v[166:167] op_sel_hi:[1,0]
	ds_write2_b32 v105, v144, v145 offset1:1
	ds_write2_b32 v105, v146, v147 offset0:2 offset1:3
	ds_write2_b32 v109, v148, v149 offset1:1
	ds_write2_b32 v109, v150, v151 offset0:2 offset1:3
	s_waitcnt lgkmcnt(0)
	s_barrier
	ds_read2_b32 v[120:121], v110 offset1:65
	ds_read2_b32 v[122:123], v110 offset0:130 offset1:195
	ds_read2_b32 v[124:125], v114 offset0:4 offset1:69
	ds_read2_b32 v[126:127], v114 offset0:134 offset1:199
	ds_read2_b32 v[128:129], v111 offset1:65
	ds_read2_b32 v[130:131], v111 offset0:130 offset1:195
	ds_read2_b32 v[132:133], v115 offset0:4 offset1:69
	ds_read2_b32 v[134:135], v115 offset0:134 offset1:199
	ds_read2_b32 v[136:137], v112 offset1:65
	ds_read2_b32 v[138:139], v112 offset0:130 offset1:195
	ds_read2_b32 v[140:141], v116 offset0:4 offset1:69
	ds_read2_b32 v[142:143], v116 offset0:134 offset1:199
	ds_read2_b32 v[144:145], v113 offset1:65
	ds_read2_b32 v[146:147], v113 offset0:130 offset1:195
	ds_read2_b32 v[148:149], v117 offset0:4 offset1:69
	ds_read2_b32 v[150:151], v117 offset0:134 offset1:199
	s_waitcnt lgkmcnt(12)
	v_cvt_pk_bf16_f32 v120, v120, v121
	v_cvt_pk_bf16_f32 v121, v122, v123
	v_cvt_pk_bf16_f32 v122, v124, v125
	v_cvt_pk_bf16_f32 v123, v126, v127
	v_add_u32_e32 v180, s96, v118
	global_store_dwordx4 v180, v[120:123], s[14:15]
	s_waitcnt lgkmcnt(8)
	v_cvt_pk_bf16_f32 v128, v128, v129
	v_cvt_pk_bf16_f32 v129, v130, v131
	v_cvt_pk_bf16_f32 v130, v132, v133
	v_cvt_pk_bf16_f32 v131, v134, v135
	v_add_u32_e32 v181, s97, v118
	global_store_dwordx4 v181, v[128:131], s[14:15]
	s_waitcnt lgkmcnt(4)
	v_cvt_pk_bf16_f32 v136, v136, v137
	v_cvt_pk_bf16_f32 v137, v138, v139
	v_cvt_pk_bf16_f32 v138, v140, v141
	v_cvt_pk_bf16_f32 v139, v142, v143
	v_add_u32_e32 v182, s98, v118
	global_store_dwordx4 v182, v[136:139], s[14:15]
	s_waitcnt lgkmcnt(0)
	v_cvt_pk_bf16_f32 v144, v144, v145
	v_cvt_pk_bf16_f32 v145, v146, v147
	v_cvt_pk_bf16_f32 v146, v148, v149
	v_cvt_pk_bf16_f32 v147, v150, v151
	v_add_u32_e32 v183, s99, v118
	global_store_dwordx4 v183, v[144:147], s[14:15]
	s_barrier
	s_lshl_b32 s92, s33, 2
	s_add_i32 s85, s85, s92
	s_branch .Lp0w_loop
.Lp0w_done:
	s_lshl_b32 s25, s85, 6
	s_lshl_b32 s35, s85, 5
	s_lshl_b32 s77, s85, 4
	s_lshl_b32 s79, s85, 1
	s_lshl_b32 s81, s85, 2
	s_branch .LBB0_24
